# v34 + V-transpose of the light prep items through an XOR-swizzled LDS tile: 16-B coalesced row loads, full 128-B line stores into VT (8 lanes per row) instead of 48 two-byte loads + 16-B pieces scatte
# speedup vs baseline: 1.0131x; 1.0097x over previous
; __device__ __forceinline__ void phase_prep(const Params& P, int l, unsigned char* lds) {
;     ...
; #pragma unroll 1
;             for (int rep = 0; rep < 6; ++rep) {
;                 const int id = tid + 512 * rep, cc = id % 384, ch = id / 384;
;                 const int col = (cc < 256) ? PA_V + cc : PC_V + (cc - 256);
;                 const bf16_t* p = proj + (size_t)(r0 + 8 * ch) * INW + col;
;                 unsigned e[8];
; #pragma unroll
;                 for (int j = 0; j < 8; ++j) e[j] = p[(size_t)j * INW];
;                 u32x4 o; o.x = e[0] | (e[1] << 16); o.y = e[2] | (e[3] << 16); o.z = e[4] | (e[5] << 16); o.w = e[6] | (e[7] << 16);
;                 bf16_t* dst = (cc < 256) ? (bf16_t*)(P.ws + WS_VTA) + ((size_t)b * 256 + cc) * TT : (bf16_t*)(P.ws + WS_VTC) + ((size_t)b * 128 + (cc - 256)) * TT;
;                 *(u32x4*)(dst + t0 + 8 * ch) = o;
;             }
.LBB0_288:
	s_or_b64 exec, exec, s[48:49]
	v_mov_b32_e32 v40, 0x1100
	v_mov_b32_e32 v41, 0x400
	v_mov_b32_e32 v30, v44
	v_mul_u32_u24_e32 v31, 0xaab, v30
	v_lshrrev_b32_e32 v31, 17, v31
	v_mul_u32_u24_e32 v32, 48, v31
	v_sub_u32_e32 v32, v30, v32
	v_cmp_gt_u32_e32 vcc, 32, v32
	s_nop 1
	v_cndmask_b32_e32 v33, v40, v41, vcc
	v_lshl_add_u32 v33, v32, 4, v33
	v_add_u32_e32 v34, s29, v31
	v_mul_u32_u24_e32 v34, 0x1600, v34
	v_add_u32_e32 v34, v34, v33
	global_load_dwordx4 v[0:3], v34, s[10:11]
	v_mul_u32_u24_e32 v24, 0x300, v31
	v_bfe_u32 v33, v31, 3, 3
	v_xor_b32_e32 v33, v32, v33
	v_lshl_add_u32 v24, v33, 4, v24
	v_add_u32_e32 v30, 512, v44
	v_mul_u32_u24_e32 v31, 0xaab, v30
	v_lshrrev_b32_e32 v31, 17, v31
	v_mul_u32_u24_e32 v32, 48, v31
	v_sub_u32_e32 v32, v30, v32
	v_cmp_gt_u32_e32 vcc, 32, v32
	s_nop 1
	v_cndmask_b32_e32 v33, v40, v41, vcc
	v_lshl_add_u32 v33, v32, 4, v33
	v_add_u32_e32 v34, s29, v31
	v_mul_u32_u24_e32 v34, 0x1600, v34
	v_add_u32_e32 v34, v34, v33
	global_load_dwordx4 v[4:7], v34, s[10:11]
	v_mul_u32_u24_e32 v25, 0x300, v31
	v_bfe_u32 v33, v31, 3, 3
	v_xor_b32_e32 v33, v32, v33
	v_lshl_add_u32 v25, v33, 4, v25
	v_add_u32_e32 v30, 1024, v44
	v_mul_u32_u24_e32 v31, 0xaab, v30
	v_lshrrev_b32_e32 v31, 17, v31
	v_mul_u32_u24_e32 v32, 48, v31
	v_sub_u32_e32 v32, v30, v32
	v_cmp_gt_u32_e32 vcc, 32, v32
	s_nop 1
	v_cndmask_b32_e32 v33, v40, v41, vcc
	v_lshl_add_u32 v33, v32, 4, v33
	v_add_u32_e32 v34, s29, v31
	v_mul_u32_u24_e32 v34, 0x1600, v34
	v_add_u32_e32 v34, v34, v33
	global_load_dwordx4 v[8:11], v34, s[10:11]
	v_mul_u32_u24_e32 v26, 0x300, v31
	v_bfe_u32 v33, v31, 3, 3
	v_xor_b32_e32 v33, v32, v33
	v_lshl_add_u32 v26, v33, 4, v26
	v_add_u32_e32 v30, 1536, v44
	v_mul_u32_u24_e32 v31, 0xaab, v30
	v_lshrrev_b32_e32 v31, 17, v31
	v_mul_u32_u24_e32 v32, 48, v31
	v_sub_u32_e32 v32, v30, v32
	v_cmp_gt_u32_e32 vcc, 32, v32
	s_nop 1
	v_cndmask_b32_e32 v33, v40, v41, vcc
	v_lshl_add_u32 v33, v32, 4, v33
	v_add_u32_e32 v34, s29, v31
	v_mul_u32_u24_e32 v34, 0x1600, v34
	v_add_u32_e32 v34, v34, v33
	global_load_dwordx4 v[12:15], v34, s[10:11]
	v_mul_u32_u24_e32 v27, 0x300, v31
	v_bfe_u32 v33, v31, 3, 3
	v_xor_b32_e32 v33, v32, v33
	v_lshl_add_u32 v27, v33, 4, v27
	v_add_u32_e32 v30, 2048, v44
	v_mul_u32_u24_e32 v31, 0xaab, v30
	v_lshrrev_b32_e32 v31, 17, v31
	v_mul_u32_u24_e32 v32, 48, v31
	v_sub_u32_e32 v32, v30, v32
	v_cmp_gt_u32_e32 vcc, 32, v32
	s_nop 1
	v_cndmask_b32_e32 v33, v40, v41, vcc
	v_lshl_add_u32 v33, v32, 4, v33
	v_add_u32_e32 v34, s29, v31
	v_mul_u32_u24_e32 v34, 0x1600, v34
	v_add_u32_e32 v34, v34, v33
	global_load_dwordx4 v[16:19], v34, s[10:11]
	v_mul_u32_u24_e32 v28, 0x300, v31
	v_bfe_u32 v33, v31, 3, 3
	v_xor_b32_e32 v33, v32, v33
	v_lshl_add_u32 v28, v33, 4, v28
	v_add_u32_e32 v30, 2560, v44
	v_mul_u32_u24_e32 v31, 0xaab, v30
	v_lshrrev_b32_e32 v31, 17, v31
	v_mul_u32_u24_e32 v32, 48, v31
	v_sub_u32_e32 v32, v30, v32
	v_cmp_gt_u32_e32 vcc, 32, v32
	s_nop 1
	v_cndmask_b32_e32 v33, v40, v41, vcc
	v_lshl_add_u32 v33, v32, 4, v33
	v_add_u32_e32 v34, s29, v31
	v_mul_u32_u24_e32 v34, 0x1600, v34
	v_add_u32_e32 v34, v34, v33
	global_load_dwordx4 v[20:23], v34, s[10:11]
	v_mul_u32_u24_e32 v29, 0x300, v31
	v_bfe_u32 v33, v31, 3, 3
	v_xor_b32_e32 v33, v32, v33
	v_lshl_add_u32 v29, v33, 4, v29
	s_waitcnt vmcnt(5)
	ds_write_b128 v24, v[0:3]
	s_waitcnt vmcnt(4)
	ds_write_b128 v25, v[4:7]
	s_waitcnt vmcnt(3)
	ds_write_b128 v26, v[8:11]
	s_waitcnt vmcnt(2)
	ds_write_b128 v27, v[12:15]
	s_waitcnt vmcnt(1)
	ds_write_b128 v28, v[16:19]
	s_waitcnt vmcnt(0)
	ds_write_b128 v29, v[20:23]
	s_waitcnt lgkmcnt(0)
	s_barrier
; __device__ __forceinline__ void phase_prep(const Params& P, int l, unsigned char* lds) {
;     ...
; #pragma unroll 1
;             for (int rep = 0; rep < 6; ++rep) {
;                 const int id = tid + 512 * rep, cc = id % 384, ch = id / 384;
;                 const int col = (cc < 256) ? PA_V + cc : PC_V + (cc - 256);
;                 const bf16_t* p = proj + (size_t)(r0 + 8 * ch) * INW + col;
;                 unsigned e[8];
; #pragma unroll
;                 for (int j = 0; j < 8; ++j) e[j] = p[(size_t)j * INW];
;                 u32x4 o; o.x = e[0] | (e[1] << 16); o.y = e[2] | (e[3] << 16); o.z = e[4] | (e[5] << 16); o.w = e[6] | (e[7] << 16);
;                 bf16_t* dst = (cc < 256) ? (bf16_t*)(P.ws + WS_VTA) + ((size_t)b * 256 + cc) * TT : (bf16_t*)(P.ws + WS_VTC) + ((size_t)b * 128 + (cc - 256)) * TT;
;                 *(u32x4*)(dst + t0 + 8 * ch) = o;
;             }
	s_lshl_b32 s12, s36, 8
	s_lshl_b32 s13, s36, 7
	s_sub_u32 s13, s13, 0x100
	s_lshl_b32 s15, s64, 1
	v_mov_b32_e32 v40, 0x17500000
	v_mov_b32_e32 v41, 0x16300000
	v_mov_b32_e32 v30, v44
	v_lshrrev_b32_e32 v31, 3, v30
	v_and_b32_e32 v30, 7, v30
	v_mul_u32_u24_e32 v32, 0x1800, v30
	v_lshrrev_b32_e32 v33, 3, v31
	v_xor_b32_e32 v33, v33, v30
	v_lshl_add_u32 v32, v33, 4, v32
	v_and_b32_e32 v33, 7, v31
	v_lshl_add_u32 v32, v33, 1, v32
	ds_read_u16 v48, v32
	ds_read_u16 v49, v32 offset:768
	ds_read_u16 v50, v32 offset:1536
	ds_read_u16 v51, v32 offset:2304
	ds_read_u16 v52, v32 offset:3072
	ds_read_u16 v53, v32 offset:3840
	ds_read_u16 v54, v32 offset:4608
	ds_read_u16 v55, v32 offset:5376
	v_cmp_gt_u32_e32 vcc, 0x100, v31
	v_add_u32_e32 v33, s12, v31
	v_add_u32_e32 v34, s13, v31
	v_cndmask_b32_e32 v33, v34, v33, vcc
	v_cndmask_b32_e32 v35, v40, v41, vcc
	v_mul_u32_u24_e32 v33, 0x1200, v33
	v_lshl_add_u32 v35, v30, 4, v35
	v_add3_u32 v24, v33, v35, s15
	s_waitcnt lgkmcnt(0)
	v_lshl_or_b32 v0, v49, 16, v48
	v_lshl_or_b32 v1, v51, 16, v50
	v_lshl_or_b32 v2, v53, 16, v52
	v_lshl_or_b32 v3, v55, 16, v54
	global_store_dwordx4 v24, v[0:3], s[0:1]
	v_add_u32_e32 v30, 512, v44
	v_lshrrev_b32_e32 v31, 3, v30
	v_and_b32_e32 v30, 7, v30
	v_mul_u32_u24_e32 v32, 0x1800, v30
	v_lshrrev_b32_e32 v33, 3, v31
	v_xor_b32_e32 v33, v33, v30
	v_lshl_add_u32 v32, v33, 4, v32
	v_and_b32_e32 v33, 7, v31
	v_lshl_add_u32 v32, v33, 1, v32
	ds_read_u16 v48, v32
	ds_read_u16 v49, v32 offset:768
	ds_read_u16 v50, v32 offset:1536
	ds_read_u16 v51, v32 offset:2304
	ds_read_u16 v52, v32 offset:3072
	ds_read_u16 v53, v32 offset:3840
	ds_read_u16 v54, v32 offset:4608
	ds_read_u16 v55, v32 offset:5376
	v_cmp_gt_u32_e32 vcc, 0x100, v31
	v_add_u32_e32 v33, s12, v31
	v_add_u32_e32 v34, s13, v31
	v_cndmask_b32_e32 v33, v34, v33, vcc
	v_cndmask_b32_e32 v35, v40, v41, vcc
	v_mul_u32_u24_e32 v33, 0x1200, v33
	v_lshl_add_u32 v35, v30, 4, v35
	v_add3_u32 v25, v33, v35, s15
	s_waitcnt lgkmcnt(0)
	v_lshl_or_b32 v4, v49, 16, v48
	v_lshl_or_b32 v5, v51, 16, v50
	v_lshl_or_b32 v6, v53, 16, v52
	v_lshl_or_b32 v7, v55, 16, v54
	global_store_dwordx4 v25, v[4:7], s[0:1]
	v_add_u32_e32 v30, 1024, v44
	v_lshrrev_b32_e32 v31, 3, v30
	v_and_b32_e32 v30, 7, v30
	v_mul_u32_u24_e32 v32, 0x1800, v30
	v_lshrrev_b32_e32 v33, 3, v31
	v_xor_b32_e32 v33, v33, v30
	v_lshl_add_u32 v32, v33, 4, v32
	v_and_b32_e32 v33, 7, v31
	v_lshl_add_u32 v32, v33, 1, v32
	ds_read_u16 v48, v32
	ds_read_u16 v49, v32 offset:768
	ds_read_u16 v50, v32 offset:1536
	ds_read_u16 v51, v32 offset:2304
	ds_read_u16 v52, v32 offset:3072
	ds_read_u16 v53, v32 offset:3840
	ds_read_u16 v54, v32 offset:4608
	ds_read_u16 v55, v32 offset:5376
	v_cmp_gt_u32_e32 vcc, 0x100, v31
	v_add_u32_e32 v33, s12, v31
	v_add_u32_e32 v34, s13, v31
	v_cndmask_b32_e32 v33, v34, v33, vcc
	v_cndmask_b32_e32 v35, v40, v41, vcc
	v_mul_u32_u24_e32 v33, 0x1200, v33
	v_lshl_add_u32 v35, v30, 4, v35
	v_add3_u32 v26, v33, v35, s15
	s_waitcnt lgkmcnt(0)
	v_lshl_or_b32 v8, v49, 16, v48
	v_lshl_or_b32 v9, v51, 16, v50
	v_lshl_or_b32 v10, v53, 16, v52
	v_lshl_or_b32 v11, v55, 16, v54
	global_store_dwordx4 v26, v[8:11], s[0:1]
	v_add_u32_e32 v30, 1536, v44
	v_lshrrev_b32_e32 v31, 3, v30
	v_and_b32_e32 v30, 7, v30
	v_mul_u32_u24_e32 v32, 0x1800, v30
	v_lshrrev_b32_e32 v33, 3, v31
	v_xor_b32_e32 v33, v33, v30
	v_lshl_add_u32 v32, v33, 4, v32
	v_and_b32_e32 v33, 7, v31
	v_lshl_add_u32 v32, v33, 1, v32
	ds_read_u16 v48, v32
	ds_read_u16 v49, v32 offset:768
	ds_read_u16 v50, v32 offset:1536
	ds_read_u16 v51, v32 offset:2304
	ds_read_u16 v52, v32 offset:3072
	ds_read_u16 v53, v32 offset:3840
	ds_read_u16 v54, v32 offset:4608
	ds_read_u16 v55, v32 offset:5376
	v_cmp_gt_u32_e32 vcc, 0x100, v31
	v_add_u32_e32 v33, s12, v31
	v_add_u32_e32 v34, s13, v31
	v_cndmask_b32_e32 v33, v34, v33, vcc
	v_cndmask_b32_e32 v35, v40, v41, vcc
	v_mul_u32_u24_e32 v33, 0x1200, v33
	v_lshl_add_u32 v35, v30, 4, v35
	v_add3_u32 v27, v33, v35, s15
	s_waitcnt lgkmcnt(0)
	v_lshl_or_b32 v12, v49, 16, v48
	v_lshl_or_b32 v13, v51, 16, v50
	v_lshl_or_b32 v14, v53, 16, v52
	v_lshl_or_b32 v15, v55, 16, v54
	global_store_dwordx4 v27, v[12:15], s[0:1]
	v_add_u32_e32 v30, 2048, v44
	v_lshrrev_b32_e32 v31, 3, v30
	v_and_b32_e32 v30, 7, v30
	v_mul_u32_u24_e32 v32, 0x1800, v30
	v_lshrrev_b32_e32 v33, 3, v31
	v_xor_b32_e32 v33, v33, v30
	v_lshl_add_u32 v32, v33, 4, v32
	v_and_b32_e32 v33, 7, v31
	v_lshl_add_u32 v32, v33, 1, v32
	ds_read_u16 v48, v32
	ds_read_u16 v49, v32 offset:768
	ds_read_u16 v50, v32 offset:1536
	ds_read_u16 v51, v32 offset:2304
	ds_read_u16 v52, v32 offset:3072
	ds_read_u16 v53, v32 offset:3840
	ds_read_u16 v54, v32 offset:4608
	ds_read_u16 v55, v32 offset:5376
	v_cmp_gt_u32_e32 vcc, 0x100, v31
	v_add_u32_e32 v33, s12, v31
	v_add_u32_e32 v34, s13, v31
	v_cndmask_b32_e32 v33, v34, v33, vcc
	v_cndmask_b32_e32 v35, v40, v41, vcc
	v_mul_u32_u24_e32 v33, 0x1200, v33
	v_lshl_add_u32 v35, v30, 4, v35
	v_add3_u32 v28, v33, v35, s15
	s_waitcnt lgkmcnt(0)
	v_lshl_or_b32 v16, v49, 16, v48
	v_lshl_or_b32 v17, v51, 16, v50
	v_lshl_or_b32 v18, v53, 16, v52
	v_lshl_or_b32 v19, v55, 16, v54
	global_store_dwordx4 v28, v[16:19], s[0:1]
	v_add_u32_e32 v30, 2560, v44
	v_lshrrev_b32_e32 v31, 3, v30
	v_and_b32_e32 v30, 7, v30
	v_mul_u32_u24_e32 v32, 0x1800, v30
	v_lshrrev_b32_e32 v33, 3, v31
	v_xor_b32_e32 v33, v33, v30
	v_lshl_add_u32 v32, v33, 4, v32
	v_and_b32_e32 v33, 7, v31
	v_lshl_add_u32 v32, v33, 1, v32
	ds_read_u16 v48, v32
	ds_read_u16 v49, v32 offset:768
	ds_read_u16 v50, v32 offset:1536
	ds_read_u16 v51, v32 offset:2304
	ds_read_u16 v52, v32 offset:3072
	ds_read_u16 v53, v32 offset:3840
	ds_read_u16 v54, v32 offset:4608
	ds_read_u16 v55, v32 offset:5376
	v_cmp_gt_u32_e32 vcc, 0x100, v31
	v_add_u32_e32 v33, s12, v31
	v_add_u32_e32 v34, s13, v31
	v_cndmask_b32_e32 v33, v34, v33, vcc
	v_cndmask_b32_e32 v35, v40, v41, vcc
	v_mul_u32_u24_e32 v33, 0x1200, v33
	v_lshl_add_u32 v35, v30, 4, v35
	v_add3_u32 v29, v33, v35, s15
	s_waitcnt lgkmcnt(0)
	v_lshl_or_b32 v20, v49, 16, v48
	v_lshl_or_b32 v21, v51, 16, v50
	v_lshl_or_b32 v22, v53, 16, v52
	v_lshl_or_b32 v23, v55, 16, v54
	global_store_dwordx4 v29, v[20:23], s[0:1]
	s_barrier
	s_branch .LBB0_227
